# scan loop edge: dead per-step address advances removed; compute waves branch straight back into their step body
# speedup vs baseline: 1.0031x; 1.0028x over previous
.LBB0_158:
	s_mov_b64 s[6:7], 0x60000
	s_add_i32 s10, s10, 1
	v_lshl_add_u64 v[38:39], v[38:39], 0, s[6:7]
	s_and_b32 s11, s10, 1
	s_cmp_lg_u32 s10, 63
	s_cbranch_scc0 .LBB0_163

.Lscan_compute:
	s_mul_i32 s11, s11, 0x12000
	s_add_i32 s6, s11, 0
	v_add_u32_e32 v0, s6, v58
	v_add_u32_e32 v2, s6, v59
	v_add_u32_e32 v3, s6, v60
	v_add_u32_e32 v142, s6, v61
	ds_read_b128 v[62:65], v0
	ds_read_b128 v[66:69], v0 offset:4096
	ds_read_b128 v[70:73], v2
	ds_read_b128 v[74:77], v2 offset:4096
	ds_read_b128 v[78:81], v3
	ds_read_b128 v[82:85], v3 offset:4096
	ds_read_b128 v[86:89], v142
	ds_read_b128 v[90:93], v142 offset:4096
	ds_read_b128 v[94:97], v0 offset:8192
	ds_read_b128 v[98:101], v0 offset:12288
	ds_read_b128 v[102:105], v2 offset:8192
	ds_read_b128 v[106:109], v2 offset:12288
	ds_read_b128 v[110:113], v3 offset:8192
	ds_read_b128 v[114:117], v3 offset:12288
	ds_read_b128 v[118:121], v142 offset:8192
	ds_read_b128 v[122:125], v142 offset:12288
	ds_read_b128 v[126:129], v0 offset:16384
	ds_read_b128 v[130:133], v0 offset:20480
	ds_read_b128 v[134:137], v2 offset:16384
	ds_read_b128 v[138:141], v2 offset:20480
	ds_read_b128 v[146:149], v3 offset:16384
	ds_read_b128 v[154:157], v3 offset:20480
	ds_read_b128 v[162:165], v142 offset:16384
	ds_read_b128 v[166:169], v142 offset:20480
	ds_read_b128 v[170:173], v0 offset:24576
	ds_read_b128 v[174:177], v0 offset:28672
	ds_read_b128 v[178:181], v2 offset:24576
	ds_read_b128 v[182:185], v2 offset:28672
	ds_read_b128 v[186:189], v3 offset:24576
	ds_read_b128 v[190:193], v3 offset:28672
	ds_read_b128 v[194:197], v142 offset:24576
	ds_read_b128 v[198:201], v142 offset:28672
	v_cvt_pk_bf16_f32 v202, v12, v13
	v_cvt_pk_bf16_f32 v203, v14, v15
	v_cvt_pk_bf16_f32 v204, v4, v5
	v_cvt_pk_bf16_f32 v205, v6, v7
	v_cvt_pk_bf16_f32 v206, v8, v9
	v_cvt_pk_bf16_f32 v207, v10, v11
	v_cvt_pk_bf16_f32 v208, v16, v17
	v_cvt_pk_bf16_f32 v209, v18, v19
	v_cvt_pk_bf16_f32 v210, v20, v21
	v_cvt_pk_bf16_f32 v211, v22, v23
	v_cvt_pk_bf16_f32 v212, v24, v25
	v_cvt_pk_bf16_f32 v213, v26, v27
	v_cvt_pk_bf16_f32 v222, v28, v29
	v_cvt_pk_bf16_f32 v223, v30, v31
	v_cvt_pk_bf16_f32 v224, v32, v33
	v_cvt_pk_bf16_f32 v225, v34, v35
	s_waitcnt lgkmcnt(14)
	v_mfma_f32_16x16x32_bf16 v[62:65], v[62:65], v[202:205], 0
	v_add3_u32 v0, s6, v56, v57
	v_add_u32_e32 v145, s6, v55
	v_add_u32_e32 v159, s6, v54
	v_mfma_f32_16x16x32_bf16 v[66:69], v[66:69], v[202:205], 0
	ds_read2st64_b32 v[2:3], v0 offset0:224 offset1:225
	ds_read2st64_b32 v[142:143], v0 offset0:226 offset1:227
	v_mfma_f32_16x16x32_bf16 v[62:65], v[70:73], v[206:209], v[62:65]
	v_mfma_f32_16x16x32_bf16 v[66:69], v[74:77], v[206:209], v[66:69]
	v_mfma_f32_16x16x32_bf16 v[70:73], v[94:97], v[202:205], 0
	v_mfma_f32_16x16x32_bf16 v[62:65], v[78:81], v[210:213], v[62:65]
	ds_read_b128 v[78:81], v145 offset:49152
	v_mfma_f32_16x16x32_bf16 v[66:69], v[82:85], v[210:213], v[66:69]
	v_mfma_f32_16x16x32_bf16 v[74:77], v[98:101], v[202:205], 0
	v_mfma_f32_16x16x32_bf16 v[70:73], v[102:105], v[206:209], v[70:73]
	v_add_u32_e32 v102, 0xe000, v0
	v_mfma_f32_16x16x32_bf16 v[62:65], v[86:89], v[222:225], v[62:65]
	v_mfma_f32_16x16x32_bf16 v[66:69], v[90:93], v[222:225], v[66:69]
	v_mfma_f32_16x16x32_bf16 v[74:77], v[106:109], v[206:209], v[74:77]
	ds_read_b128 v[82:85], v159 offset:49152
	ds_read2st64_b32 v[226:227], v0 offset0:240 offset1:241
	ds_read2st64_b32 v[228:229], v0 offset0:242 offset1:243
	ds_read_b128 v[86:89], v145 offset:51200
	ds_read_b128 v[90:93], v159 offset:51200
	ds_read2st64_b32 v[230:231], v102 offset0:32 offset1:33
	ds_read2st64_b32 v[232:233], v102 offset0:34 offset1:35
	ds_read_b128 v[94:97], v145 offset:53248
	ds_read_b128 v[98:101], v159 offset:53248
	ds_read2st64_b32 v[234:235], v102 offset0:48 offset1:49
	ds_read2st64_b32 v[236:237], v102 offset0:50 offset1:51
	ds_read_b128 v[102:105], v145 offset:55296
	ds_read_b128 v[106:109], v159 offset:55296
	v_mfma_f32_16x16x32_bf16 v[70:73], v[110:113], v[210:213], v[70:73]
	v_mfma_f32_16x16x32_bf16 v[74:77], v[114:117], v[210:213], v[74:77]
	v_mfma_f32_16x16x32_bf16 v[70:73], v[118:121], v[222:225], v[70:73]
	v_mfma_f32_16x16x32_bf16 v[74:77], v[122:125], v[222:225], v[74:77]
	v_mfma_f32_16x16x32_bf16 v[110:113], v[126:129], v[202:205], 0
	v_mfma_f32_16x16x32_bf16 v[114:117], v[130:133], v[202:205], 0
	s_waitcnt lgkmcnt(14)
	v_mfma_f32_16x16x32_bf16 v[118:121], v[170:173], v[202:205], 0
	v_mfma_f32_16x16x32_bf16 v[122:125], v[174:177], v[202:205], 0
	v_mfma_f32_16x16x32_bf16 v[110:113], v[134:137], v[206:209], v[110:113]
	v_mfma_f32_16x16x32_bf16 v[114:117], v[138:141], v[206:209], v[114:117]
	v_mfma_f32_16x16x32_bf16 v[118:121], v[178:181], v[206:209], v[118:121]
	v_mfma_f32_16x16x32_bf16 v[122:125], v[182:185], v[206:209], v[122:125]
	v_mfma_f32_16x16x32_bf16 v[110:113], v[146:149], v[210:213], v[110:113]
	v_mfma_f32_16x16x32_bf16 v[114:117], v[154:157], v[210:213], v[114:117]
	v_mfma_f32_16x16x32_bf16 v[118:121], v[186:189], v[210:213], v[118:121]
	v_mfma_f32_16x16x32_bf16 v[122:125], v[190:193], v[210:213], v[122:125]
	v_mfma_f32_16x16x32_bf16 v[110:113], v[162:165], v[222:225], v[110:113]
	v_mfma_f32_16x16x32_bf16 v[114:117], v[166:169], v[222:225], v[114:117]
	v_mfma_f32_16x16x32_bf16 v[118:121], v[194:197], v[222:225], v[118:121]
	v_mfma_f32_16x16x32_bf16 v[122:125], v[198:201], v[222:225], v[122:125]
	ds_read_b128 v[126:129], v145 offset:32768
	ds_read_b128 v[130:133], v159 offset:32768
	ds_read_b128 v[134:137], v145 offset:34816
	ds_read_b128 v[138:141], v159 offset:34816
	ds_read_b128 v[146:149], v145 offset:36864
	ds_read_b128 v[154:157], v159 offset:36864
	ds_read_b128 v[162:165], v145 offset:38912
	ds_read_b128 v[166:169], v159 offset:38912
	ds_read_b128 v[170:173], v145 offset:40960
	ds_read_b128 v[174:177], v159 offset:40960
	ds_read_b128 v[178:181], v145 offset:43008
	ds_read_b128 v[182:185], v159 offset:43008
	ds_read_b128 v[186:189], v145 offset:45056
	ds_read_b128 v[190:193], v159 offset:45056
	ds_read_b128 v[194:197], v145 offset:47104
	ds_read_b128 v[198:201], v159 offset:47104
	v_pk_add_f32 v[2:3], v[2:3], v[62:63] neg_lo:[0,1] neg_hi:[0,1]
	v_pk_add_f32 v[64:65], v[142:143], v[64:65] neg_lo:[0,1] neg_hi:[0,1]
	s_waitcnt lgkmcnt(14)
	v_pk_add_f32 v[66:67], v[226:227], v[66:67] neg_lo:[0,1] neg_hi:[0,1]
	v_pk_add_f32 v[68:69], v[228:229], v[68:69] neg_lo:[0,1] neg_hi:[0,1]
	v_pk_add_f32 v[70:71], v[230:231], v[70:71] neg_lo:[0,1] neg_hi:[0,1]
	v_cvt_pk_bf16_f32 v62, v2, v3
	v_cvt_pk_bf16_f32 v63, v64, v65
	v_cvt_pk_bf16_f32 v64, v66, v67
	v_cvt_pk_bf16_f32 v65, v68, v69
	v_pk_add_f32 v[142:143], v[232:233], v[72:73] neg_lo:[0,1] neg_hi:[0,1]
	v_cvt_pk_bf16_f32 v66, v70, v71
	v_mfma_f32_16x16x32_bf16 v[70:73], v[78:81], v[62:65], v[110:113]
	v_readlane_b32 s6, v37, s10
	v_pk_add_f32 v[74:75], v[234:235], v[74:75] neg_lo:[0,1] neg_hi:[0,1]
	v_pk_add_f32 v[76:77], v[236:237], v[76:77] neg_lo:[0,1] neg_hi:[0,1]
	v_pk_mul_f32 v[6:7], v[6:7], s[6:7] op_sel_hi:[1,0]
	v_pk_mul_f32 v[4:5], v[4:5], s[6:7] op_sel_hi:[1,0]
	v_cvt_pk_bf16_f32 v67, v142, v143
	v_cvt_pk_bf16_f32 v68, v74, v75
	v_cvt_pk_bf16_f32 v69, v76, v77
	s_waitcnt lgkmcnt(13)
	v_mfma_f32_16x16x32_bf16 v[2:5], v[134:137], v[62:65], v[4:7]
	v_mul_f32_e64 v14, v14, s6
	v_mul_f32_e64 v15, v15, s6
	v_pk_mul_f32 v[12:13], v[12:13], s[6:7] op_sel_hi:[1,0]
	v_pk_mul_f32 v[10:11], v[10:11], s[6:7] op_sel_hi:[1,0]
	v_mfma_f32_16x16x32_bf16 v[70:73], v[82:85], v[66:69], v[70:73]
	v_mul_f32_e64 v8, v8, s6
	v_mul_f32_e64 v9, v9, s6
	v_pk_mul_f32 v[18:19], v[18:19], s[6:7] op_sel_hi:[1,0]
	v_pk_mul_f32 v[16:17], v[16:17], s[6:7] op_sel_hi:[1,0]
	v_mfma_f32_16x16x32_bf16 v[74:77], v[86:89], v[62:65], v[114:117]
	v_mul_f32_e64 v22, v22, s6
	v_mul_f32_e64 v23, v23, s6
	s_nop 0
	v_cvt_pk_bf16_f32 v0, v70, s0
	v_pk_mul_f32 v[20:21], v[20:21], s[6:7] op_sel_hi:[1,0]
	s_waitcnt lgkmcnt(12)
	v_mfma_f32_16x16x32_bf16 v[4:7], v[138:141], v[66:69], v[2:5]
	v_mul_f32_e64 v26, v26, s6
	v_mul_f32_e64 v27, v27, s6
	v_pk_mul_f32 v[24:25], v[24:25], s[6:7] op_sel_hi:[1,0]
	v_pk_mul_f32 v[30:31], v[30:31], s[6:7] op_sel_hi:[1,0]
	v_lshl_add_u64 v[2:3], s[2:3], 0, v[38:39]
	v_add_co_u32_e32 v70, vcc, s52, v2
	v_pk_mul_f32 v[28:29], v[28:29], s[6:7] op_sel_hi:[1,0]
	v_pk_mul_f32 v[34:35], v[34:35], s[6:7] op_sel_hi:[1,0]
	v_pk_mul_f32 v[32:33], v[32:33], s[6:7] op_sel_hi:[1,0]
	global_store_short v[2:3], v0, off
	v_cvt_pk_bf16_f32 v0, v71, s0
	v_addc_co_u32_e32 v71, vcc, 0, v3, vcc
	s_movk_i32 s6, 0x3000
	global_store_short v[70:71], v0, off offset:2048
	v_add_co_u32_e32 v70, vcc, s6, v2
	v_mfma_f32_16x16x32_bf16 v[74:77], v[90:93], v[66:69], v[74:77]
	v_cvt_pk_bf16_f32 v0, v72, s0
	v_addc_co_u32_e32 v71, vcc, 0, v3, vcc
	s_movk_i32 s6, 0x4000
	global_store_short v[70:71], v0, off
	v_add_co_u32_e32 v70, vcc, s6, v2
	v_cvt_pk_bf16_f32 v0, v73, s0
	s_nop 0
	v_addc_co_u32_e32 v71, vcc, 0, v3, vcc
	global_store_short v[70:71], v0, off offset:2048
	v_add_co_u32_e32 v70, vcc, s51, v2
	v_mfma_f32_16x16x32_bf16 v[78:81], v[94:97], v[62:65], v[118:121]
	v_cvt_pk_bf16_f32 v0, v74, s0
	v_addc_co_u32_e32 v71, vcc, 0, v3, vcc
	s_mov_b32 s6, 0x19000
	global_store_short v[70:71], v0, off
	v_add_co_u32_e32 v70, vcc, s6, v2
	s_mov_b32 s6, 0x1b000
	s_nop 0
	v_addc_co_u32_e32 v71, vcc, 0, v3, vcc
	v_mfma_f32_16x16x32_bf16 v[82:85], v[102:105], v[62:65], v[122:125]
	v_cvt_pk_bf16_f32 v0, v75, s0
	global_store_short v[70:71], v0, off offset:2048
	v_cvt_pk_bf16_f32 v0, v76, s0
	v_mfma_f32_16x16x32_bf16 v[12:15], v[126:129], v[62:65], v[12:15]
	s_waitcnt lgkmcnt(11)
	v_mfma_f32_16x16x32_bf16 v[8:11], v[146:149], v[62:65], v[8:11]
	s_waitcnt lgkmcnt(9)
	v_mfma_f32_16x16x32_bf16 v[16:19], v[162:165], v[62:65], v[16:19]
	s_waitcnt lgkmcnt(7)
	v_mfma_f32_16x16x32_bf16 v[20:23], v[170:173], v[62:65], v[20:23]
	s_waitcnt lgkmcnt(5)
	v_mfma_f32_16x16x32_bf16 v[24:27], v[178:181], v[62:65], v[24:27]
	s_waitcnt lgkmcnt(3)
	v_mfma_f32_16x16x32_bf16 v[28:31], v[186:189], v[62:65], v[28:31]
	s_waitcnt lgkmcnt(1)
	v_mfma_f32_16x16x32_bf16 v[32:35], v[194:197], v[62:65], v[32:35]
	v_add_co_u32_e32 v62, vcc, s6, v2
	s_mov_b32 s6, 0x1c000
	v_mfma_f32_16x16x32_bf16 v[78:81], v[98:101], v[66:69], v[78:81]
	v_addc_co_u32_e32 v63, vcc, 0, v3, vcc
	global_store_short v[62:63], v0, off
	v_add_co_u32_e32 v62, vcc, s6, v2
	v_cvt_pk_bf16_f32 v0, v77, s0
	s_nop 0
	v_addc_co_u32_e32 v63, vcc, 0, v3, vcc
	s_mov_b32 s6, 0x30000
	global_store_short v[62:63], v0, off offset:2048
	v_add_co_u32_e32 v62, vcc, s6, v2
	v_cvt_pk_bf16_f32 v0, v78, s0
	s_nop 0
	v_addc_co_u32_e32 v63, vcc, 0, v3, vcc
	s_mov_b32 s6, 0x31000
	global_store_short v[62:63], v0, off
	v_add_co_u32_e32 v62, vcc, s6, v2
	v_cvt_pk_bf16_f32 v0, v79, s0
	s_nop 0
	v_addc_co_u32_e32 v63, vcc, 0, v3, vcc
	s_mov_b32 s6, 0x33000
	global_store_short v[62:63], v0, off offset:2048
	v_add_co_u32_e32 v62, vcc, s6, v2
	v_mfma_f32_16x16x32_bf16 v[82:85], v[106:109], v[66:69], v[82:85]
	v_cvt_pk_bf16_f32 v0, v80, s0
	v_addc_co_u32_e32 v63, vcc, 0, v3, vcc
	s_mov_b32 s6, 0x34000
	global_store_short v[62:63], v0, off
	v_add_co_u32_e32 v62, vcc, s6, v2
	v_cvt_pk_bf16_f32 v0, v81, s0
	s_nop 0
	v_addc_co_u32_e32 v63, vcc, 0, v3, vcc
	s_mov_b32 s6, 0x48000
	global_store_short v[62:63], v0, off offset:2048
	v_add_co_u32_e32 v62, vcc, s6, v2
	v_cvt_pk_bf16_f32 v0, v82, s0
	s_nop 0
	v_addc_co_u32_e32 v63, vcc, 0, v3, vcc
	s_mov_b32 s6, 0x49000
	global_store_short v[62:63], v0, off
	v_add_co_u32_e32 v62, vcc, s6, v2
	v_cvt_pk_bf16_f32 v0, v83, s0
	s_nop 0
	v_addc_co_u32_e32 v63, vcc, 0, v3, vcc
	global_store_short v[62:63], v0, off offset:2048
	v_add_co_u32_e32 v62, vcc, 0x4b000, v2
	v_cvt_pk_bf16_f32 v0, v84, s0
	s_nop 0
	v_addc_co_u32_e32 v63, vcc, 0, v3, vcc
	v_add_co_u32_e32 v2, vcc, 0x4c000, v2
	global_store_short v[62:63], v0, off
	v_cvt_pk_bf16_f32 v0, v85, s0
	v_addc_co_u32_e32 v3, vcc, 0, v3, vcc
	v_mfma_f32_16x16x32_bf16 v[12:15], v[130:133], v[66:69], v[12:15]
	global_store_short v[2:3], v0, off offset:2048
	s_waitcnt vmcnt(16) lgkmcnt(0)
	s_barrier
	v_mfma_f32_16x16x32_bf16 v[8:11], v[154:157], v[66:69], v[8:11]
	v_mfma_f32_16x16x32_bf16 v[16:19], v[166:169], v[66:69], v[16:19]
	v_mfma_f32_16x16x32_bf16 v[20:23], v[174:177], v[66:69], v[20:23]
	v_mfma_f32_16x16x32_bf16 v[24:27], v[182:185], v[66:69], v[24:27]
	v_mfma_f32_16x16x32_bf16 v[28:31], v[190:193], v[66:69], v[28:31]
	s_waitcnt lgkmcnt(0)
	v_mfma_f32_16x16x32_bf16 v[32:35], v[198:201], v[66:69], v[32:35]
	s_mov_b64 s[6:7], 0x60000
	s_add_i32 s10, s10, 1
	v_lshl_add_u64 v[38:39], v[38:39], 0, s[6:7]
	s_and_b32 s11, s10, 1
	s_cmp_lg_u32 s10, 63
	s_cbranch_scc1 .Lscan_compute
	s_branch .LBB0_163
